# EpiMerge epilogue: gates/prev loads prefetched 8 units ahead into free VGPRs, counted vmcnt, flat->global (on top of v7)
# speedup vs baseline: 1.0114x; 1.0114x over previous
;     __device__ __forceinline__ void operator()(const f32x4 (&acc)[2][2][4][2], const Unit& u, int wr, int wc, int fr, int fq) const {
;         const int row0 = u.pm * BM + wr * 64 + fr, col0 = u.pn * BM + wc * 32 + 8 * fq;
; #pragma unroll
;         for (int ai = 0; ai < 2; ++ai)
; #pragma unroll
;             for (int m = 0; m < 4; ++m)
; #pragma unroll
;                 for (int bj = 0; bj < 2; ++bj) {
;                     const unsigned row = (unsigned)(row0 + ai * HALF + m * 16);
;                     const int col = col0 + bj * HALF;
;                     const h16x8 gv = *(const h16x8*)(gates + row * DM + col);
;                     h16x8 pv = {0, 0, 0, 0, 0, 0, 0, 0};
;                     if (add) pv = *(const h16x8*)(Mg + row * DM + col);
.LBB0_143:
	v_lshl_or_b32 v150, s89, 8, v158
	v_lshl_add_u32 v32, s92, 18, v157
	v_add_lshl_u32 v181, v32, v150, 1
	v_add_u32_e32 v180, 0x0, v181
	global_load_dwordx4 v[204:207], v180, s[16:17]
	global_load_dwordx4 v[208:211], v180, s[84:85]
	v_add_u32_e32 v180, 0x0, v181
	global_load_dwordx4 v[212:215], v180, s[16:17] offset:256
	global_load_dwordx4 v[216:219], v180, s[84:85] offset:256
	v_add_u32_e32 v180, 0x8000, v181
	global_load_dwordx4 v[220:223], v180, s[16:17]
	global_load_dwordx4 v[224:227], v180, s[84:85]
	v_add_u32_e32 v180, 0x8000, v181
	global_load_dwordx4 v[228:231], v180, s[16:17] offset:256
	global_load_dwordx4 v[232:235], v180, s[84:85] offset:256
	v_add_u32_e32 v180, 0x10000, v181
	global_load_dwordx4 v[236:239], v180, s[16:17]
	global_load_dwordx4 v[240:243], v180, s[84:85]
	v_add_u32_e32 v180, 0x10000, v181
	global_load_dwordx4 v[244:247], v180, s[16:17] offset:256
	global_load_dwordx4 v[248:251], v180, s[84:85] offset:256
	v_add_u32_e32 v180, 0x18000, v181
	global_load_dwordx4 v[164:167], v180, s[16:17]
	global_load_dwordx4 v[168:171], v180, s[84:85]
	v_add_u32_e32 v180, 0x18000, v181
	global_load_dwordx4 v[172:175], v180, s[16:17] offset:256
	global_load_dwordx4 v[176:179], v180, s[84:85] offset:256
	v_lshl_add_u64 v[130:131], v[32:33], 1, s[16:17]
	v_ashrrev_i32_e32 v151, 31, v150
	v_lshl_add_u64 v[152:153], v[150:151], 1, v[130:131]
	s_waitcnt vmcnt(14)
	v_mov_b32_e32 v130, v204
	v_mov_b32_e32 v131, v205
	v_mov_b32_e32 v132, v206
	v_mov_b32_e32 v133, v207
	v_cndmask_b32_e64 v134, 0, 1, s[12:13]
	v_cmp_ne_u32_e64 s[6:7], 1, v134
	s_andn2_b64 vcc, exec, s[12:13]
	v_lshl_add_u64 v[154:155], v[32:33], 1, s[84:85]
	s_cbranch_vccnz .LBB0_145
	v_lshl_add_u64 v[134:135], v[150:151], 1, v[154:155]
	v_mov_b32_e32 v134, v208
	v_mov_b32_e32 v135, v209
	v_mov_b32_e32 v136, v210
	v_mov_b32_e32 v137, v211
	s_branch .LBB0_146

;     __device__ __forceinline__ void operator()(const f32x4 (&acc)[2][2][4][2], const Unit& u, int wr, int wc, int fr, int fq) const {
;     ...
;                 for (int bj = 0; bj < 2; ++bj) {
;                     const unsigned row = (unsigned)(row0 + ai * HALF + m * 16);
;                     const int col = col0 + bj * HALF;
;                     const h16x8 gv = *(const h16x8*)(gates + row * DM + col);
;                     h16x8 pv = {0, 0, 0, 0, 0, 0, 0, 0};
;                     if (add) pv = *(const h16x8*)(Mg + row * DM + col);
;                     h16x8 o;
; #pragma unroll
;                     for (int n = 0; n < 2; ++n)
; #pragma unroll
;                         for (int j = 0; j < 4; ++j) o[4 * n + j] = (h16)((float)pv[4 * n + j] + (float)gv[4 * n + j] * acc[ai][bj][m][n][j]);
;                     *(h16x8*)(Mg + row * DM + col) = o;
.LBB0_146:
	v_add_u32_e32 v180, 0x40000, v181
	global_load_dwordx4 v[204:207], v180, s[16:17]
	global_load_dwordx4 v[208:211], v180, s[84:85]
	v_cvt_f32_f16_sdwa v161, v134 dst_sel:DWORD dst_unused:UNUSED_PAD src0_sel:WORD_1
	v_cvt_f32_f16_e32 v160, v134
	v_cvt_f32_f16_sdwa v163, v130 dst_sel:DWORD dst_unused:UNUSED_PAD src0_sel:WORD_1
	v_cvt_f32_f16_e32 v162, v130
	v_cvt_f32_f16_e32 v134, v131
	v_cvt_f32_f16_e32 v130, v132
	s_and_b64 vcc, exec, s[6:7]
	v_pk_fma_f32 v[126:127], v[126:127], v[162:163], v[160:161]
	v_cvt_f32_f16_sdwa v161, v135 dst_sel:DWORD dst_unused:UNUSED_PAD src0_sel:WORD_1
	v_cvt_f32_f16_e32 v160, v135
	v_cvt_f32_f16_sdwa v135, v131 dst_sel:DWORD dst_unused:UNUSED_PAD src0_sel:WORD_1
	v_cvt_pk_f16_f32 v126, v126, v127
	v_cvt_f32_f16_sdwa v131, v132 dst_sel:DWORD dst_unused:UNUSED_PAD src0_sel:WORD_1
	v_pk_fma_f32 v[128:129], v[128:129], v[134:135], v[160:161]
	s_nop 0
	v_cvt_pk_f16_f32 v127, v128, v129
	v_cvt_f32_f16_sdwa v129, v136 dst_sel:DWORD dst_unused:UNUSED_PAD src0_sel:WORD_1
	v_cvt_f32_f16_e32 v128, v136
	v_pk_fma_f32 v[122:123], v[122:123], v[130:131], v[128:129]
	s_nop 0
	v_cvt_pk_f16_f32 v128, v122, v123
	v_cvt_f32_f16_sdwa v123, v137 dst_sel:DWORD dst_unused:UNUSED_PAD src0_sel:WORD_1
	v_cvt_f32_f16_e32 v122, v137
	v_cvt_f32_f16_sdwa v131, v133 dst_sel:DWORD dst_unused:UNUSED_PAD src0_sel:WORD_1
	v_cvt_f32_f16_e32 v130, v133
	v_pk_fma_f32 v[122:123], v[124:125], v[130:131], v[122:123]
	s_nop 0
	v_cvt_pk_f16_f32 v129, v122, v123
	v_lshl_add_u64 v[130:131], v[150:151], 1, v[154:155]
	global_store_dwordx4 v[130:131], v[126:129], off
	s_waitcnt vmcnt(15)
	v_mov_b32_e32 v122, v212
	v_mov_b32_e32 v123, v213
	v_mov_b32_e32 v124, v214
	v_mov_b32_e32 v125, v215
	s_cbranch_vccnz .LBB0_148
	v_mov_b32_e32 v126, v216
	v_mov_b32_e32 v127, v217
	v_mov_b32_e32 v128, v218
	v_mov_b32_e32 v129, v219
	s_branch .LBB0_149

;     __device__ __forceinline__ void operator()(const f32x4 (&acc)[2][2][4][2], const Unit& u, int wr, int wc, int fr, int fq) const {
;     ...
;                 for (int bj = 0; bj < 2; ++bj) {
;                     const unsigned row = (unsigned)(row0 + ai * HALF + m * 16);
;                     const int col = col0 + bj * HALF;
;                     const h16x8 gv = *(const h16x8*)(gates + row * DM + col);
;                     h16x8 pv = {0, 0, 0, 0, 0, 0, 0, 0};
;                     if (add) pv = *(const h16x8*)(Mg + row * DM + col);
;                     h16x8 o;
; #pragma unroll
;                     for (int n = 0; n < 2; ++n)
; #pragma unroll
;                         for (int j = 0; j < 4; ++j) o[4 * n + j] = (h16)((float)pv[4 * n + j] + (float)gv[4 * n + j] * acc[ai][bj][m][n][j]);
;                     *(h16x8*)(Mg + row * DM + col) = o;
.LBB0_149:
	v_add_u32_e32 v180, 0x40000, v181
	global_load_dwordx4 v[212:215], v180, s[16:17] offset:256
	global_load_dwordx4 v[216:219], v180, s[84:85] offset:256
	v_cvt_f32_f16_sdwa v133, v126 dst_sel:DWORD dst_unused:UNUSED_PAD src0_sel:WORD_1
	v_cvt_f32_f16_e32 v132, v126
	v_cvt_f32_f16_sdwa v135, v122 dst_sel:DWORD dst_unused:UNUSED_PAD src0_sel:WORD_1
	v_cvt_f32_f16_e32 v134, v122
	v_cvt_f32_f16_e32 v126, v123
	v_cvt_f32_f16_e32 v122, v124
	s_and_b64 vcc, exec, s[6:7]
	v_pk_fma_f32 v[118:119], v[118:119], v[134:135], v[132:133]
	v_cvt_f32_f16_sdwa v133, v127 dst_sel:DWORD dst_unused:UNUSED_PAD src0_sel:WORD_1
	v_cvt_f32_f16_e32 v132, v127
	v_cvt_f32_f16_sdwa v127, v123 dst_sel:DWORD dst_unused:UNUSED_PAD src0_sel:WORD_1
	v_cvt_pk_f16_f32 v118, v118, v119
	v_cvt_f32_f16_sdwa v123, v124 dst_sel:DWORD dst_unused:UNUSED_PAD src0_sel:WORD_1
	v_pk_fma_f32 v[120:121], v[120:121], v[126:127], v[132:133]
	s_nop 0
	v_cvt_pk_f16_f32 v119, v120, v121
	v_cvt_f32_f16_sdwa v121, v128 dst_sel:DWORD dst_unused:UNUSED_PAD src0_sel:WORD_1
	v_cvt_f32_f16_e32 v120, v128
	v_pk_fma_f32 v[114:115], v[114:115], v[122:123], v[120:121]
	s_nop 0
	v_cvt_pk_f16_f32 v120, v114, v115
	v_cvt_f32_f16_sdwa v115, v129 dst_sel:DWORD dst_unused:UNUSED_PAD src0_sel:WORD_1
	v_cvt_f32_f16_e32 v114, v129
	v_cvt_f32_f16_sdwa v123, v125 dst_sel:DWORD dst_unused:UNUSED_PAD src0_sel:WORD_1
	v_cvt_f32_f16_e32 v122, v125
	v_pk_fma_f32 v[114:115], v[116:117], v[122:123], v[114:115]
	s_nop 0
	v_cvt_pk_f16_f32 v121, v114, v115
	global_store_dwordx4 v[130:131], v[118:121], off offset:256
	s_nop 1
	v_or_b32_e32 v118, 0x4000, v32
	v_mov_b32_e32 v119, v33
	v_lshl_add_u64 v[114:115], v[118:119], 1, s[16:17]
	v_lshl_add_u64 v[122:123], v[150:151], 1, v[114:115]
	s_waitcnt vmcnt(16)
	v_mov_b32_e32 v114, v220
	v_mov_b32_e32 v115, v221
	v_mov_b32_e32 v116, v222
	v_mov_b32_e32 v117, v223
	v_lshl_add_u64 v[124:125], v[118:119], 1, s[84:85]
	s_cbranch_vccnz .LBB0_151
	v_lshl_add_u64 v[118:119], v[150:151], 1, v[124:125]
	v_mov_b32_e32 v118, v224
	v_mov_b32_e32 v119, v225
	v_mov_b32_e32 v120, v226
	v_mov_b32_e32 v121, v227
	s_branch .LBB0_152

;     __device__ __forceinline__ void operator()(const f32x4 (&acc)[2][2][4][2], const Unit& u, int wr, int wc, int fr, int fq) const {
;     ...
;                 for (int bj = 0; bj < 2; ++bj) {
;                     const unsigned row = (unsigned)(row0 + ai * HALF + m * 16);
;                     const int col = col0 + bj * HALF;
;                     const h16x8 gv = *(const h16x8*)(gates + row * DM + col);
;                     h16x8 pv = {0, 0, 0, 0, 0, 0, 0, 0};
;                     if (add) pv = *(const h16x8*)(Mg + row * DM + col);
;                     h16x8 o;
; #pragma unroll
;                     for (int n = 0; n < 2; ++n)
; #pragma unroll
;                         for (int j = 0; j < 4; ++j) o[4 * n + j] = (h16)((float)pv[4 * n + j] + (float)gv[4 * n + j] * acc[ai][bj][m][n][j]);
;                     *(h16x8*)(Mg + row * DM + col) = o;
.LBB0_152:
	v_add_u32_e32 v180, 0x48000, v181
	global_load_dwordx4 v[220:223], v180, s[16:17]
	global_load_dwordx4 v[224:227], v180, s[84:85]
	v_cvt_f32_f16_sdwa v127, v118 dst_sel:DWORD dst_unused:UNUSED_PAD src0_sel:WORD_1
	v_cvt_f32_f16_e32 v126, v118
	v_cvt_f32_f16_sdwa v129, v114 dst_sel:DWORD dst_unused:UNUSED_PAD src0_sel:WORD_1
	v_cvt_f32_f16_e32 v128, v114
	v_cvt_f32_f16_e32 v118, v115
	v_cvt_f32_f16_e32 v114, v116
	s_and_b64 vcc, exec, s[6:7]
	v_pk_fma_f32 v[110:111], v[110:111], v[128:129], v[126:127]
	v_cvt_f32_f16_sdwa v127, v119 dst_sel:DWORD dst_unused:UNUSED_PAD src0_sel:WORD_1
	v_cvt_f32_f16_e32 v126, v119
	v_cvt_f32_f16_sdwa v119, v115 dst_sel:DWORD dst_unused:UNUSED_PAD src0_sel:WORD_1
	v_cvt_pk_f16_f32 v110, v110, v111
	v_cvt_f32_f16_sdwa v115, v116 dst_sel:DWORD dst_unused:UNUSED_PAD src0_sel:WORD_1
	v_pk_fma_f32 v[112:113], v[112:113], v[118:119], v[126:127]
	s_nop 0
	v_cvt_pk_f16_f32 v111, v112, v113
	v_cvt_f32_f16_sdwa v113, v120 dst_sel:DWORD dst_unused:UNUSED_PAD src0_sel:WORD_1
	v_cvt_f32_f16_e32 v112, v120
	v_pk_fma_f32 v[106:107], v[106:107], v[114:115], v[112:113]
	s_nop 0
	v_cvt_pk_f16_f32 v112, v106, v107
	v_cvt_f32_f16_sdwa v107, v121 dst_sel:DWORD dst_unused:UNUSED_PAD src0_sel:WORD_1
	v_cvt_f32_f16_e32 v106, v121
	v_cvt_f32_f16_sdwa v115, v117 dst_sel:DWORD dst_unused:UNUSED_PAD src0_sel:WORD_1
	v_cvt_f32_f16_e32 v114, v117
	v_pk_fma_f32 v[106:107], v[108:109], v[114:115], v[106:107]
	s_nop 0
	v_cvt_pk_f16_f32 v113, v106, v107
	v_lshl_add_u64 v[114:115], v[150:151], 1, v[124:125]
	global_store_dwordx4 v[114:115], v[110:113], off
	s_waitcnt vmcnt(17)
	v_mov_b32_e32 v106, v228
	v_mov_b32_e32 v107, v229
	v_mov_b32_e32 v108, v230
	v_mov_b32_e32 v109, v231
	s_cbranch_vccnz .LBB0_154
	v_mov_b32_e32 v110, v232
	v_mov_b32_e32 v111, v233
	v_mov_b32_e32 v112, v234
	v_mov_b32_e32 v113, v235
	s_branch .LBB0_155

;     __device__ __forceinline__ void operator()(const f32x4 (&acc)[2][2][4][2], const Unit& u, int wr, int wc, int fr, int fq) const {
;     ...
;                 for (int bj = 0; bj < 2; ++bj) {
;                     const unsigned row = (unsigned)(row0 + ai * HALF + m * 16);
;                     const int col = col0 + bj * HALF;
;                     const h16x8 gv = *(const h16x8*)(gates + row * DM + col);
;                     h16x8 pv = {0, 0, 0, 0, 0, 0, 0, 0};
;                     if (add) pv = *(const h16x8*)(Mg + row * DM + col);
;                     h16x8 o;
; #pragma unroll
;                     for (int n = 0; n < 2; ++n)
; #pragma unroll
;                         for (int j = 0; j < 4; ++j) o[4 * n + j] = (h16)((float)pv[4 * n + j] + (float)gv[4 * n + j] * acc[ai][bj][m][n][j]);
;                     *(h16x8*)(Mg + row * DM + col) = o;
.LBB0_155:
	v_add_u32_e32 v180, 0x48000, v181
	global_load_dwordx4 v[228:231], v180, s[16:17] offset:256
	global_load_dwordx4 v[232:235], v180, s[84:85] offset:256
	v_cvt_f32_f16_sdwa v117, v110 dst_sel:DWORD dst_unused:UNUSED_PAD src0_sel:WORD_1
	v_cvt_f32_f16_e32 v116, v110
	v_cvt_f32_f16_sdwa v119, v106 dst_sel:DWORD dst_unused:UNUSED_PAD src0_sel:WORD_1
	v_cvt_f32_f16_e32 v118, v106
	v_cvt_f32_f16_e32 v110, v107
	v_cvt_f32_f16_e32 v106, v108
	s_and_b64 vcc, exec, s[6:7]
	v_pk_fma_f32 v[102:103], v[102:103], v[118:119], v[116:117]
	v_cvt_f32_f16_sdwa v117, v111 dst_sel:DWORD dst_unused:UNUSED_PAD src0_sel:WORD_1
	v_cvt_f32_f16_e32 v116, v111
	v_cvt_f32_f16_sdwa v111, v107 dst_sel:DWORD dst_unused:UNUSED_PAD src0_sel:WORD_1
	v_cvt_pk_f16_f32 v102, v102, v103
	v_cvt_f32_f16_sdwa v107, v108 dst_sel:DWORD dst_unused:UNUSED_PAD src0_sel:WORD_1
	v_pk_fma_f32 v[104:105], v[104:105], v[110:111], v[116:117]
	s_nop 0
	v_cvt_pk_f16_f32 v103, v104, v105
	v_cvt_f32_f16_sdwa v105, v112 dst_sel:DWORD dst_unused:UNUSED_PAD src0_sel:WORD_1
	v_cvt_f32_f16_e32 v104, v112
	v_pk_fma_f32 v[98:99], v[98:99], v[106:107], v[104:105]
	s_nop 0
	v_cvt_pk_f16_f32 v104, v98, v99
	v_cvt_f32_f16_sdwa v99, v113 dst_sel:DWORD dst_unused:UNUSED_PAD src0_sel:WORD_1
	v_cvt_f32_f16_e32 v98, v113
	v_cvt_f32_f16_sdwa v107, v109 dst_sel:DWORD dst_unused:UNUSED_PAD src0_sel:WORD_1
	v_cvt_f32_f16_e32 v106, v109
	v_pk_fma_f32 v[98:99], v[100:101], v[106:107], v[98:99]
	s_nop 0
	v_cvt_pk_f16_f32 v105, v98, v99
	global_store_dwordx4 v[114:115], v[102:105], off offset:256
	s_nop 1
	v_or_b32_e32 v102, 0x8000, v32
	v_mov_b32_e32 v103, v33
	v_lshl_add_u64 v[98:99], v[102:103], 1, s[16:17]
	v_lshl_add_u64 v[106:107], v[150:151], 1, v[98:99]
	s_waitcnt vmcnt(18)
	v_mov_b32_e32 v98, v236
	v_mov_b32_e32 v99, v237
	v_mov_b32_e32 v100, v238
	v_mov_b32_e32 v101, v239
	v_lshl_add_u64 v[108:109], v[102:103], 1, s[84:85]
	s_cbranch_vccnz .LBB0_157
	v_lshl_add_u64 v[102:103], v[150:151], 1, v[108:109]
	v_mov_b32_e32 v102, v240
	v_mov_b32_e32 v103, v241
	v_mov_b32_e32 v104, v242
	v_mov_b32_e32 v105, v243
	s_branch .LBB0_158

;     __device__ __forceinline__ void operator()(const f32x4 (&acc)[2][2][4][2], const Unit& u, int wr, int wc, int fr, int fq) const {
;     ...
;                 for (int bj = 0; bj < 2; ++bj) {
;                     const unsigned row = (unsigned)(row0 + ai * HALF + m * 16);
;                     const int col = col0 + bj * HALF;
;                     const h16x8 gv = *(const h16x8*)(gates + row * DM + col);
;                     h16x8 pv = {0, 0, 0, 0, 0, 0, 0, 0};
;                     if (add) pv = *(const h16x8*)(Mg + row * DM + col);
;                     h16x8 o;
; #pragma unroll
;                     for (int n = 0; n < 2; ++n)
; #pragma unroll
;                         for (int j = 0; j < 4; ++j) o[4 * n + j] = (h16)((float)pv[4 * n + j] + (float)gv[4 * n + j] * acc[ai][bj][m][n][j]);
;                     *(h16x8*)(Mg + row * DM + col) = o;
.LBB0_158:
	v_add_u32_e32 v180, 0x50000, v181
	global_load_dwordx4 v[236:239], v180, s[16:17]
	global_load_dwordx4 v[240:243], v180, s[84:85]
	v_cvt_f32_f16_sdwa v111, v102 dst_sel:DWORD dst_unused:UNUSED_PAD src0_sel:WORD_1
	v_cvt_f32_f16_e32 v110, v102
	v_cvt_f32_f16_sdwa v113, v98 dst_sel:DWORD dst_unused:UNUSED_PAD src0_sel:WORD_1
	v_cvt_f32_f16_e32 v112, v98
	v_cvt_f32_f16_e32 v102, v99
	v_cvt_f32_f16_e32 v98, v100
	s_and_b64 vcc, exec, s[6:7]
	v_pk_fma_f32 v[94:95], v[94:95], v[112:113], v[110:111]
	v_cvt_f32_f16_sdwa v111, v103 dst_sel:DWORD dst_unused:UNUSED_PAD src0_sel:WORD_1
	v_cvt_f32_f16_e32 v110, v103
	v_cvt_f32_f16_sdwa v103, v99 dst_sel:DWORD dst_unused:UNUSED_PAD src0_sel:WORD_1
	v_cvt_pk_f16_f32 v94, v94, v95
	v_cvt_f32_f16_sdwa v99, v100 dst_sel:DWORD dst_unused:UNUSED_PAD src0_sel:WORD_1
	v_pk_fma_f32 v[96:97], v[96:97], v[102:103], v[110:111]
	s_nop 0
	v_cvt_pk_f16_f32 v95, v96, v97
	v_cvt_f32_f16_sdwa v97, v104 dst_sel:DWORD dst_unused:UNUSED_PAD src0_sel:WORD_1
	v_cvt_f32_f16_e32 v96, v104
	v_pk_fma_f32 v[90:91], v[90:91], v[98:99], v[96:97]
	s_nop 0
	v_cvt_pk_f16_f32 v96, v90, v91
	v_cvt_f32_f16_sdwa v91, v105 dst_sel:DWORD dst_unused:UNUSED_PAD src0_sel:WORD_1
	v_cvt_f32_f16_e32 v90, v105
	v_cvt_f32_f16_sdwa v99, v101 dst_sel:DWORD dst_unused:UNUSED_PAD src0_sel:WORD_1
	v_cvt_f32_f16_e32 v98, v101
	v_pk_fma_f32 v[90:91], v[92:93], v[98:99], v[90:91]
	s_nop 0
	v_cvt_pk_f16_f32 v97, v90, v91
	v_lshl_add_u64 v[98:99], v[150:151], 1, v[108:109]
	global_store_dwordx4 v[98:99], v[94:97], off
	s_waitcnt vmcnt(19)
	v_mov_b32_e32 v90, v244
	v_mov_b32_e32 v91, v245
	v_mov_b32_e32 v92, v246
	v_mov_b32_e32 v93, v247
	s_cbranch_vccnz .LBB0_160
	v_mov_b32_e32 v94, v248
	v_mov_b32_e32 v95, v249
	v_mov_b32_e32 v96, v250
	v_mov_b32_e32 v97, v251
	s_branch .LBB0_161

;     __device__ __forceinline__ void operator()(const f32x4 (&acc)[2][2][4][2], const Unit& u, int wr, int wc, int fr, int fq) const {
;     ...
;                 for (int bj = 0; bj < 2; ++bj) {
;                     const unsigned row = (unsigned)(row0 + ai * HALF + m * 16);
;                     const int col = col0 + bj * HALF;
;                     const h16x8 gv = *(const h16x8*)(gates + row * DM + col);
;                     h16x8 pv = {0, 0, 0, 0, 0, 0, 0, 0};
;                     if (add) pv = *(const h16x8*)(Mg + row * DM + col);
;                     h16x8 o;
; #pragma unroll
;                     for (int n = 0; n < 2; ++n)
; #pragma unroll
;                         for (int j = 0; j < 4; ++j) o[4 * n + j] = (h16)((float)pv[4 * n + j] + (float)gv[4 * n + j] * acc[ai][bj][m][n][j]);
;                     *(h16x8*)(Mg + row * DM + col) = o;
.LBB0_161:
	v_add_u32_e32 v180, 0x50000, v181
	global_load_dwordx4 v[244:247], v180, s[16:17] offset:256
	global_load_dwordx4 v[248:251], v180, s[84:85] offset:256
	v_cvt_f32_f16_sdwa v101, v94 dst_sel:DWORD dst_unused:UNUSED_PAD src0_sel:WORD_1
	v_cvt_f32_f16_e32 v100, v94
	v_cvt_f32_f16_sdwa v103, v90 dst_sel:DWORD dst_unused:UNUSED_PAD src0_sel:WORD_1
	v_cvt_f32_f16_e32 v102, v90
	v_cvt_f32_f16_e32 v94, v91
	v_cvt_f32_f16_e32 v90, v92
	s_and_b64 vcc, exec, s[6:7]
	v_pk_fma_f32 v[86:87], v[86:87], v[102:103], v[100:101]
	v_cvt_f32_f16_sdwa v101, v95 dst_sel:DWORD dst_unused:UNUSED_PAD src0_sel:WORD_1
	v_cvt_f32_f16_e32 v100, v95
	v_cvt_f32_f16_sdwa v95, v91 dst_sel:DWORD dst_unused:UNUSED_PAD src0_sel:WORD_1
	v_cvt_pk_f16_f32 v86, v86, v87
	v_cvt_f32_f16_sdwa v91, v92 dst_sel:DWORD dst_unused:UNUSED_PAD src0_sel:WORD_1
	v_pk_fma_f32 v[88:89], v[88:89], v[94:95], v[100:101]
	s_nop 0
	v_cvt_pk_f16_f32 v87, v88, v89
	v_cvt_f32_f16_sdwa v89, v96 dst_sel:DWORD dst_unused:UNUSED_PAD src0_sel:WORD_1
	v_cvt_f32_f16_e32 v88, v96
	v_pk_fma_f32 v[82:83], v[82:83], v[90:91], v[88:89]
	s_nop 0
	v_cvt_pk_f16_f32 v88, v82, v83
	v_cvt_f32_f16_sdwa v83, v97 dst_sel:DWORD dst_unused:UNUSED_PAD src0_sel:WORD_1
	v_cvt_f32_f16_e32 v82, v97
	v_cvt_f32_f16_sdwa v91, v93 dst_sel:DWORD dst_unused:UNUSED_PAD src0_sel:WORD_1
	v_cvt_f32_f16_e32 v90, v93
	v_pk_fma_f32 v[82:83], v[84:85], v[90:91], v[82:83]
	s_nop 0
	v_cvt_pk_f16_f32 v89, v82, v83
	global_store_dwordx4 v[98:99], v[86:89], off offset:256
	s_nop 1
	v_or_b32_e32 v86, 0xc000, v32
	v_mov_b32_e32 v87, v33
	v_lshl_add_u64 v[82:83], v[86:87], 1, s[16:17]
	v_lshl_add_u64 v[90:91], v[150:151], 1, v[82:83]
	s_waitcnt vmcnt(20)
	v_mov_b32_e32 v82, v164
	v_mov_b32_e32 v83, v165
	v_mov_b32_e32 v84, v166
	v_mov_b32_e32 v85, v167
	v_lshl_add_u64 v[92:93], v[86:87], 1, s[84:85]
	s_cbranch_vccnz .LBB0_163
	v_lshl_add_u64 v[86:87], v[150:151], 1, v[92:93]
	v_mov_b32_e32 v86, v168
	v_mov_b32_e32 v87, v169
	v_mov_b32_e32 v88, v170
	v_mov_b32_e32 v89, v171
	s_branch .LBB0_164

;     __device__ __forceinline__ void operator()(const f32x4 (&acc)[2][2][4][2], const Unit& u, int wr, int wc, int fr, int fq) const {
;     ...
;                 for (int bj = 0; bj < 2; ++bj) {
;                     const unsigned row = (unsigned)(row0 + ai * HALF + m * 16);
;                     const int col = col0 + bj * HALF;
;                     const h16x8 gv = *(const h16x8*)(gates + row * DM + col);
;                     h16x8 pv = {0, 0, 0, 0, 0, 0, 0, 0};
;                     if (add) pv = *(const h16x8*)(Mg + row * DM + col);
;                     h16x8 o;
; #pragma unroll
;                     for (int n = 0; n < 2; ++n)
; #pragma unroll
;                         for (int j = 0; j < 4; ++j) o[4 * n + j] = (h16)((float)pv[4 * n + j] + (float)gv[4 * n + j] * acc[ai][bj][m][n][j]);
;                     *(h16x8*)(Mg + row * DM + col) = o;
.LBB0_164:
	v_add_u32_e32 v180, 0x58000, v181
	global_load_dwordx4 v[164:167], v180, s[16:17]
	global_load_dwordx4 v[168:171], v180, s[84:85]
	v_cvt_f32_f16_sdwa v95, v86 dst_sel:DWORD dst_unused:UNUSED_PAD src0_sel:WORD_1
	v_cvt_f32_f16_e32 v94, v86
	v_cvt_f32_f16_sdwa v97, v82 dst_sel:DWORD dst_unused:UNUSED_PAD src0_sel:WORD_1
	v_cvt_f32_f16_e32 v96, v82
	v_cvt_f32_f16_e32 v86, v83
	v_cvt_f32_f16_e32 v82, v84
	s_and_b64 vcc, exec, s[6:7]
	v_pk_fma_f32 v[78:79], v[78:79], v[96:97], v[94:95]
	v_cvt_f32_f16_sdwa v95, v87 dst_sel:DWORD dst_unused:UNUSED_PAD src0_sel:WORD_1
	v_cvt_f32_f16_e32 v94, v87
	v_cvt_f32_f16_sdwa v87, v83 dst_sel:DWORD dst_unused:UNUSED_PAD src0_sel:WORD_1
	v_cvt_pk_f16_f32 v78, v78, v79
	v_cvt_f32_f16_sdwa v83, v84 dst_sel:DWORD dst_unused:UNUSED_PAD src0_sel:WORD_1
	v_pk_fma_f32 v[80:81], v[80:81], v[86:87], v[94:95]
	s_nop 0
	v_cvt_pk_f16_f32 v79, v80, v81
	v_cvt_f32_f16_sdwa v81, v88 dst_sel:DWORD dst_unused:UNUSED_PAD src0_sel:WORD_1
	v_cvt_f32_f16_e32 v80, v88
	v_pk_fma_f32 v[74:75], v[74:75], v[82:83], v[80:81]
	s_nop 0
	v_cvt_pk_f16_f32 v80, v74, v75
	v_cvt_f32_f16_sdwa v75, v89 dst_sel:DWORD dst_unused:UNUSED_PAD src0_sel:WORD_1
	v_cvt_f32_f16_e32 v74, v89
	v_cvt_f32_f16_sdwa v83, v85 dst_sel:DWORD dst_unused:UNUSED_PAD src0_sel:WORD_1
	v_cvt_f32_f16_e32 v82, v85
	v_pk_fma_f32 v[74:75], v[76:77], v[82:83], v[74:75]
	s_nop 0
	v_cvt_pk_f16_f32 v81, v74, v75
	v_lshl_add_u64 v[82:83], v[150:151], 1, v[92:93]
	global_store_dwordx4 v[82:83], v[78:81], off
	s_waitcnt vmcnt(21)
	v_mov_b32_e32 v74, v172
	v_mov_b32_e32 v75, v173
	v_mov_b32_e32 v76, v174
	v_mov_b32_e32 v77, v175
	s_cbranch_vccnz .LBB0_166
	v_mov_b32_e32 v78, v176
	v_mov_b32_e32 v79, v177
	v_mov_b32_e32 v80, v178
	v_mov_b32_e32 v81, v179
	s_branch .LBB0_167

;     __device__ __forceinline__ void operator()(const f32x4 (&acc)[2][2][4][2], const Unit& u, int wr, int wc, int fr, int fq) const {
;     ...
;                 for (int bj = 0; bj < 2; ++bj) {
;                     const unsigned row = (unsigned)(row0 + ai * HALF + m * 16);
;                     const int col = col0 + bj * HALF;
;                     const h16x8 gv = *(const h16x8*)(gates + row * DM + col);
;                     h16x8 pv = {0, 0, 0, 0, 0, 0, 0, 0};
;                     if (add) pv = *(const h16x8*)(Mg + row * DM + col);
;                     h16x8 o;
; #pragma unroll
;                     for (int n = 0; n < 2; ++n)
; #pragma unroll
;                         for (int j = 0; j < 4; ++j) o[4 * n + j] = (h16)((float)pv[4 * n + j] + (float)gv[4 * n + j] * acc[ai][bj][m][n][j]);
;                     *(h16x8*)(Mg + row * DM + col) = o;
.LBB0_167:
	v_add_u32_e32 v180, 0x58000, v181
	global_load_dwordx4 v[172:175], v180, s[16:17] offset:256
	global_load_dwordx4 v[176:179], v180, s[84:85] offset:256
	v_cvt_f32_f16_sdwa v85, v78 dst_sel:DWORD dst_unused:UNUSED_PAD src0_sel:WORD_1
	v_cvt_f32_f16_e32 v84, v78
	v_cvt_f32_f16_sdwa v87, v74 dst_sel:DWORD dst_unused:UNUSED_PAD src0_sel:WORD_1
	v_cvt_f32_f16_e32 v86, v74
	v_cvt_f32_f16_e32 v78, v75
	v_cvt_f32_f16_e32 v74, v76
	s_and_b64 vcc, exec, s[6:7]
	v_pk_fma_f32 v[70:71], v[70:71], v[86:87], v[84:85]
	v_cvt_f32_f16_sdwa v85, v79 dst_sel:DWORD dst_unused:UNUSED_PAD src0_sel:WORD_1
	v_cvt_f32_f16_e32 v84, v79
	v_cvt_f32_f16_sdwa v79, v75 dst_sel:DWORD dst_unused:UNUSED_PAD src0_sel:WORD_1
	v_cvt_pk_f16_f32 v70, v70, v71
	v_cvt_f32_f16_sdwa v75, v76 dst_sel:DWORD dst_unused:UNUSED_PAD src0_sel:WORD_1
	v_pk_fma_f32 v[72:73], v[72:73], v[78:79], v[84:85]
	s_nop 0
	v_cvt_pk_f16_f32 v71, v72, v73
	v_cvt_f32_f16_sdwa v73, v80 dst_sel:DWORD dst_unused:UNUSED_PAD src0_sel:WORD_1
	v_cvt_f32_f16_e32 v72, v80
	v_pk_fma_f32 v[66:67], v[66:67], v[74:75], v[72:73]
	s_nop 0
	v_cvt_pk_f16_f32 v72, v66, v67
	v_cvt_f32_f16_sdwa v67, v81 dst_sel:DWORD dst_unused:UNUSED_PAD src0_sel:WORD_1
	v_cvt_f32_f16_e32 v66, v81
	v_cvt_f32_f16_sdwa v75, v77 dst_sel:DWORD dst_unused:UNUSED_PAD src0_sel:WORD_1
	v_cvt_f32_f16_e32 v74, v77
	v_pk_fma_f32 v[66:67], v[68:69], v[74:75], v[66:67]
	s_nop 0
	v_cvt_pk_f16_f32 v73, v66, v67
	global_store_dwordx4 v[82:83], v[70:73], off offset:256
	s_nop 1
	v_add_u32_e32 v70, 0x20000, v32
	v_mov_b32_e32 v71, v33
	v_lshl_add_u64 v[66:67], v[70:71], 1, s[16:17]
	v_lshl_add_u64 v[74:75], v[150:151], 1, v[66:67]
	s_waitcnt vmcnt(22)
	v_mov_b32_e32 v66, v204
	v_mov_b32_e32 v67, v205
	v_mov_b32_e32 v68, v206
	v_mov_b32_e32 v69, v207
	v_lshl_add_u64 v[76:77], v[70:71], 1, s[84:85]
	s_cbranch_vccnz .LBB0_169
	v_lshl_add_u64 v[70:71], v[150:151], 1, v[76:77]
	v_mov_b32_e32 v70, v208
	v_mov_b32_e32 v71, v209
	v_mov_b32_e32 v72, v210
	v_mov_b32_e32 v73, v211
	s_branch .LBB0_170

;     __device__ __forceinline__ void operator()(const f32x4 (&acc)[2][2][4][2], const Unit& u, int wr, int wc, int fr, int fq) const {
;     ...
;                 for (int bj = 0; bj < 2; ++bj) {
;                     const unsigned row = (unsigned)(row0 + ai * HALF + m * 16);
;                     const int col = col0 + bj * HALF;
;                     const h16x8 gv = *(const h16x8*)(gates + row * DM + col);
;                     h16x8 pv = {0, 0, 0, 0, 0, 0, 0, 0};
;                     if (add) pv = *(const h16x8*)(Mg + row * DM + col);
;                     h16x8 o;
; #pragma unroll
;                     for (int n = 0; n < 2; ++n)
; #pragma unroll
;                         for (int j = 0; j < 4; ++j) o[4 * n + j] = (h16)((float)pv[4 * n + j] + (float)gv[4 * n + j] * acc[ai][bj][m][n][j]);
;                     *(h16x8*)(Mg + row * DM + col) = o;
.LBB0_170:
	s_nop 0
	v_cvt_f32_f16_sdwa v79, v70 dst_sel:DWORD dst_unused:UNUSED_PAD src0_sel:WORD_1
	v_cvt_f32_f16_e32 v78, v70
	v_cvt_f32_f16_sdwa v81, v66 dst_sel:DWORD dst_unused:UNUSED_PAD src0_sel:WORD_1
	v_cvt_f32_f16_e32 v80, v66
	v_cvt_f32_f16_e32 v70, v67
	v_cvt_f32_f16_e32 v66, v68
	s_and_b64 vcc, exec, s[6:7]
	v_pk_fma_f32 v[62:63], v[62:63], v[80:81], v[78:79]
	v_cvt_f32_f16_sdwa v79, v71 dst_sel:DWORD dst_unused:UNUSED_PAD src0_sel:WORD_1
	v_cvt_f32_f16_e32 v78, v71
	v_cvt_f32_f16_sdwa v71, v67 dst_sel:DWORD dst_unused:UNUSED_PAD src0_sel:WORD_1
	v_cvt_pk_f16_f32 v62, v62, v63
	v_cvt_f32_f16_sdwa v67, v68 dst_sel:DWORD dst_unused:UNUSED_PAD src0_sel:WORD_1
	v_pk_fma_f32 v[64:65], v[64:65], v[70:71], v[78:79]
	s_nop 0
	v_cvt_pk_f16_f32 v63, v64, v65
	v_cvt_f32_f16_sdwa v65, v72 dst_sel:DWORD dst_unused:UNUSED_PAD src0_sel:WORD_1
	v_cvt_f32_f16_e32 v64, v72
	v_pk_fma_f32 v[58:59], v[58:59], v[66:67], v[64:65]
	s_nop 0
	v_cvt_pk_f16_f32 v64, v58, v59
	v_cvt_f32_f16_sdwa v59, v73 dst_sel:DWORD dst_unused:UNUSED_PAD src0_sel:WORD_1
	v_cvt_f32_f16_e32 v58, v73
	v_cvt_f32_f16_sdwa v67, v69 dst_sel:DWORD dst_unused:UNUSED_PAD src0_sel:WORD_1
	v_cvt_f32_f16_e32 v66, v69
	v_pk_fma_f32 v[58:59], v[60:61], v[66:67], v[58:59]
	s_nop 0
	v_cvt_pk_f16_f32 v65, v58, v59
	v_lshl_add_u64 v[66:67], v[150:151], 1, v[76:77]
	global_store_dwordx4 v[66:67], v[62:65], off
	s_waitcnt vmcnt(20)
	v_mov_b32_e32 v58, v212
	v_mov_b32_e32 v59, v213
	v_mov_b32_e32 v60, v214
	v_mov_b32_e32 v61, v215
	s_cbranch_vccnz .LBB0_172
	v_mov_b32_e32 v62, v216
	v_mov_b32_e32 v63, v217
	v_mov_b32_e32 v64, v218
	v_mov_b32_e32 v65, v219
	s_branch .LBB0_173

;     __device__ __forceinline__ void operator()(const f32x4 (&acc)[2][2][4][2], const Unit& u, int wr, int wc, int fr, int fq) const {
;     ...
;                 for (int bj = 0; bj < 2; ++bj) {
;                     const unsigned row = (unsigned)(row0 + ai * HALF + m * 16);
;                     const int col = col0 + bj * HALF;
;                     const h16x8 gv = *(const h16x8*)(gates + row * DM + col);
;                     h16x8 pv = {0, 0, 0, 0, 0, 0, 0, 0};
;                     if (add) pv = *(const h16x8*)(Mg + row * DM + col);
;                     h16x8 o;
; #pragma unroll
;                     for (int n = 0; n < 2; ++n)
; #pragma unroll
;                         for (int j = 0; j < 4; ++j) o[4 * n + j] = (h16)((float)pv[4 * n + j] + (float)gv[4 * n + j] * acc[ai][bj][m][n][j]);
;                     *(h16x8*)(Mg + row * DM + col) = o;
.LBB0_173:
	s_nop 0
	v_cvt_f32_f16_sdwa v69, v62 dst_sel:DWORD dst_unused:UNUSED_PAD src0_sel:WORD_1
	v_cvt_f32_f16_e32 v68, v62
	v_cvt_f32_f16_sdwa v71, v58 dst_sel:DWORD dst_unused:UNUSED_PAD src0_sel:WORD_1
	v_cvt_f32_f16_e32 v70, v58
	v_cvt_f32_f16_e32 v62, v59
	v_cvt_f32_f16_e32 v58, v60
	s_and_b64 vcc, exec, s[6:7]
	v_pk_fma_f32 v[54:55], v[54:55], v[70:71], v[68:69]
	v_cvt_f32_f16_sdwa v69, v63 dst_sel:DWORD dst_unused:UNUSED_PAD src0_sel:WORD_1
	v_cvt_f32_f16_e32 v68, v63
	v_cvt_f32_f16_sdwa v63, v59 dst_sel:DWORD dst_unused:UNUSED_PAD src0_sel:WORD_1
	v_cvt_pk_f16_f32 v54, v54, v55
	v_cvt_f32_f16_sdwa v59, v60 dst_sel:DWORD dst_unused:UNUSED_PAD src0_sel:WORD_1
	v_pk_fma_f32 v[56:57], v[56:57], v[62:63], v[68:69]
	s_nop 0
	v_cvt_pk_f16_f32 v55, v56, v57
	v_cvt_f32_f16_sdwa v57, v64 dst_sel:DWORD dst_unused:UNUSED_PAD src0_sel:WORD_1
	v_cvt_f32_f16_e32 v56, v64
	v_pk_fma_f32 v[50:51], v[50:51], v[58:59], v[56:57]
	s_nop 0
	v_cvt_pk_f16_f32 v56, v50, v51
	v_cvt_f32_f16_sdwa v51, v65 dst_sel:DWORD dst_unused:UNUSED_PAD src0_sel:WORD_1
	v_cvt_f32_f16_e32 v50, v65
	v_cvt_f32_f16_sdwa v59, v61 dst_sel:DWORD dst_unused:UNUSED_PAD src0_sel:WORD_1
	v_cvt_f32_f16_e32 v58, v61
	v_pk_fma_f32 v[50:51], v[52:53], v[58:59], v[50:51]
	s_nop 0
	v_cvt_pk_f16_f32 v57, v50, v51
	global_store_dwordx4 v[66:67], v[54:57], off offset:256
	s_nop 1
	v_add_u32_e32 v54, 0x24000, v32
	v_mov_b32_e32 v55, v33
	v_lshl_add_u64 v[50:51], v[54:55], 1, s[16:17]
	v_lshl_add_u64 v[58:59], v[150:151], 1, v[50:51]
	s_waitcnt vmcnt(18)
	v_mov_b32_e32 v50, v220
	v_mov_b32_e32 v51, v221
	v_mov_b32_e32 v52, v222
	v_mov_b32_e32 v53, v223
	v_lshl_add_u64 v[60:61], v[54:55], 1, s[84:85]
	s_cbranch_vccnz .LBB0_175
	v_lshl_add_u64 v[54:55], v[150:151], 1, v[60:61]
	v_mov_b32_e32 v54, v224
	v_mov_b32_e32 v55, v225
	v_mov_b32_e32 v56, v226
	v_mov_b32_e32 v57, v227
	s_branch .LBB0_176

;     __device__ __forceinline__ void operator()(const f32x4 (&acc)[2][2][4][2], const Unit& u, int wr, int wc, int fr, int fq) const {
;     ...
;                 for (int bj = 0; bj < 2; ++bj) {
;                     const unsigned row = (unsigned)(row0 + ai * HALF + m * 16);
;                     const int col = col0 + bj * HALF;
;                     const h16x8 gv = *(const h16x8*)(gates + row * DM + col);
;                     h16x8 pv = {0, 0, 0, 0, 0, 0, 0, 0};
;                     if (add) pv = *(const h16x8*)(Mg + row * DM + col);
;                     h16x8 o;
; #pragma unroll
;                     for (int n = 0; n < 2; ++n)
; #pragma unroll
;                         for (int j = 0; j < 4; ++j) o[4 * n + j] = (h16)((float)pv[4 * n + j] + (float)gv[4 * n + j] * acc[ai][bj][m][n][j]);
;                     *(h16x8*)(Mg + row * DM + col) = o;
.LBB0_176:
	s_nop 0
	v_cvt_f32_f16_sdwa v63, v54 dst_sel:DWORD dst_unused:UNUSED_PAD src0_sel:WORD_1
	v_cvt_f32_f16_e32 v62, v54
	v_cvt_f32_f16_sdwa v65, v50 dst_sel:DWORD dst_unused:UNUSED_PAD src0_sel:WORD_1
	v_cvt_f32_f16_e32 v64, v50
	v_cvt_f32_f16_e32 v54, v51
	v_cvt_f32_f16_e32 v50, v52
	s_and_b64 vcc, exec, s[6:7]
	v_pk_fma_f32 v[46:47], v[46:47], v[64:65], v[62:63]
	v_cvt_f32_f16_sdwa v63, v55 dst_sel:DWORD dst_unused:UNUSED_PAD src0_sel:WORD_1
	v_cvt_f32_f16_e32 v62, v55
	v_cvt_f32_f16_sdwa v55, v51 dst_sel:DWORD dst_unused:UNUSED_PAD src0_sel:WORD_1
	v_cvt_pk_f16_f32 v46, v46, v47
	v_cvt_f32_f16_sdwa v51, v52 dst_sel:DWORD dst_unused:UNUSED_PAD src0_sel:WORD_1
	v_pk_fma_f32 v[48:49], v[48:49], v[54:55], v[62:63]
	s_nop 0
	v_cvt_pk_f16_f32 v47, v48, v49
	v_cvt_f32_f16_sdwa v49, v56 dst_sel:DWORD dst_unused:UNUSED_PAD src0_sel:WORD_1
	v_cvt_f32_f16_e32 v48, v56
	v_pk_fma_f32 v[42:43], v[42:43], v[50:51], v[48:49]
	s_nop 0
	v_cvt_pk_f16_f32 v48, v42, v43
	v_cvt_f32_f16_sdwa v43, v57 dst_sel:DWORD dst_unused:UNUSED_PAD src0_sel:WORD_1
	v_cvt_f32_f16_e32 v42, v57
	v_cvt_f32_f16_sdwa v51, v53 dst_sel:DWORD dst_unused:UNUSED_PAD src0_sel:WORD_1
	v_cvt_f32_f16_e32 v50, v53
	v_pk_fma_f32 v[42:43], v[44:45], v[50:51], v[42:43]
	s_nop 0
	v_cvt_pk_f16_f32 v49, v42, v43
	v_lshl_add_u64 v[50:51], v[150:151], 1, v[60:61]
	global_store_dwordx4 v[50:51], v[46:49], off
	s_waitcnt vmcnt(16)
	v_mov_b32_e32 v42, v228
	v_mov_b32_e32 v43, v229
	v_mov_b32_e32 v44, v230
	v_mov_b32_e32 v45, v231
	s_cbranch_vccnz .LBB0_178
	v_mov_b32_e32 v46, v232
	v_mov_b32_e32 v47, v233
	v_mov_b32_e32 v48, v234
	v_mov_b32_e32 v49, v235
	s_branch .LBB0_179

;     __device__ __forceinline__ void operator()(const f32x4 (&acc)[2][2][4][2], const Unit& u, int wr, int wc, int fr, int fq) const {
;     ...
;                 for (int bj = 0; bj < 2; ++bj) {
;                     const unsigned row = (unsigned)(row0 + ai * HALF + m * 16);
;                     const int col = col0 + bj * HALF;
;                     const h16x8 gv = *(const h16x8*)(gates + row * DM + col);
;                     h16x8 pv = {0, 0, 0, 0, 0, 0, 0, 0};
;                     if (add) pv = *(const h16x8*)(Mg + row * DM + col);
;                     h16x8 o;
; #pragma unroll
;                     for (int n = 0; n < 2; ++n)
; #pragma unroll
;                         for (int j = 0; j < 4; ++j) o[4 * n + j] = (h16)((float)pv[4 * n + j] + (float)gv[4 * n + j] * acc[ai][bj][m][n][j]);
;                     *(h16x8*)(Mg + row * DM + col) = o;
.LBB0_179:
	s_nop 0
	v_cvt_f32_f16_sdwa v53, v46 dst_sel:DWORD dst_unused:UNUSED_PAD src0_sel:WORD_1
	v_cvt_f32_f16_e32 v52, v46
	v_cvt_f32_f16_sdwa v55, v42 dst_sel:DWORD dst_unused:UNUSED_PAD src0_sel:WORD_1
	v_cvt_f32_f16_e32 v54, v42
	v_cvt_f32_f16_e32 v46, v43
	v_cvt_f32_f16_e32 v42, v44
	s_and_b64 vcc, exec, s[6:7]
	v_pk_fma_f32 v[38:39], v[38:39], v[54:55], v[52:53]
	v_cvt_f32_f16_sdwa v53, v47 dst_sel:DWORD dst_unused:UNUSED_PAD src0_sel:WORD_1
	v_cvt_f32_f16_e32 v52, v47
	v_cvt_f32_f16_sdwa v47, v43 dst_sel:DWORD dst_unused:UNUSED_PAD src0_sel:WORD_1
	v_cvt_pk_f16_f32 v38, v38, v39
	v_cvt_f32_f16_sdwa v43, v44 dst_sel:DWORD dst_unused:UNUSED_PAD src0_sel:WORD_1
	v_pk_fma_f32 v[40:41], v[40:41], v[46:47], v[52:53]
	s_nop 0
	v_cvt_pk_f16_f32 v39, v40, v41
	v_cvt_f32_f16_sdwa v41, v48 dst_sel:DWORD dst_unused:UNUSED_PAD src0_sel:WORD_1
	v_cvt_f32_f16_e32 v40, v48
	v_pk_fma_f32 v[34:35], v[34:35], v[42:43], v[40:41]
	s_nop 0
	v_cvt_pk_f16_f32 v40, v34, v35
	v_cvt_f32_f16_sdwa v35, v49 dst_sel:DWORD dst_unused:UNUSED_PAD src0_sel:WORD_1
	v_cvt_f32_f16_e32 v34, v49
	v_cvt_f32_f16_sdwa v43, v45 dst_sel:DWORD dst_unused:UNUSED_PAD src0_sel:WORD_1
	v_cvt_f32_f16_e32 v42, v45
	v_pk_fma_f32 v[34:35], v[36:37], v[42:43], v[34:35]
	s_nop 0
	v_cvt_pk_f16_f32 v41, v34, v35
	global_store_dwordx4 v[50:51], v[38:41], off offset:256
	s_nop 1
	v_add_u32_e32 v38, 0x28000, v32
	v_mov_b32_e32 v39, v33
	v_lshl_add_u64 v[34:35], v[38:39], 1, s[16:17]
	v_lshl_add_u64 v[42:43], v[150:151], 1, v[34:35]
	s_waitcnt vmcnt(14)
	v_mov_b32_e32 v34, v236
	v_mov_b32_e32 v35, v237
	v_mov_b32_e32 v36, v238
	v_mov_b32_e32 v37, v239
	v_lshl_add_u64 v[44:45], v[38:39], 1, s[84:85]
	s_cbranch_vccnz .LBB0_181
	v_lshl_add_u64 v[38:39], v[150:151], 1, v[44:45]
	v_mov_b32_e32 v38, v240
	v_mov_b32_e32 v39, v241
	v_mov_b32_e32 v40, v242
	v_mov_b32_e32 v41, v243
	s_branch .LBB0_182

;     __device__ __forceinline__ void operator()(const f32x4 (&acc)[2][2][4][2], const Unit& u, int wr, int wc, int fr, int fq) const {
;     ...
;                 for (int bj = 0; bj < 2; ++bj) {
;                     const unsigned row = (unsigned)(row0 + ai * HALF + m * 16);
;                     const int col = col0 + bj * HALF;
;                     const h16x8 gv = *(const h16x8*)(gates + row * DM + col);
;                     h16x8 pv = {0, 0, 0, 0, 0, 0, 0, 0};
;                     if (add) pv = *(const h16x8*)(Mg + row * DM + col);
;                     h16x8 o;
; #pragma unroll
;                     for (int n = 0; n < 2; ++n)
; #pragma unroll
;                         for (int j = 0; j < 4; ++j) o[4 * n + j] = (h16)((float)pv[4 * n + j] + (float)gv[4 * n + j] * acc[ai][bj][m][n][j]);
;                     *(h16x8*)(Mg + row * DM + col) = o;
.LBB0_182:
	s_nop 0
	v_cvt_f32_f16_sdwa v47, v38 dst_sel:DWORD dst_unused:UNUSED_PAD src0_sel:WORD_1
	v_cvt_f32_f16_e32 v46, v38
	v_cvt_f32_f16_sdwa v49, v34 dst_sel:DWORD dst_unused:UNUSED_PAD src0_sel:WORD_1
	v_cvt_f32_f16_e32 v48, v34
	v_cvt_f32_f16_e32 v38, v35
	v_cvt_f32_f16_e32 v34, v36
	s_and_b64 vcc, exec, s[6:7]
	v_pk_fma_f32 v[28:29], v[28:29], v[48:49], v[46:47]
	v_cvt_f32_f16_sdwa v47, v39 dst_sel:DWORD dst_unused:UNUSED_PAD src0_sel:WORD_1
	v_cvt_f32_f16_e32 v46, v39
	v_cvt_f32_f16_sdwa v39, v35 dst_sel:DWORD dst_unused:UNUSED_PAD src0_sel:WORD_1
	v_cvt_pk_f16_f32 v28, v28, v29
	v_cvt_f32_f16_sdwa v35, v36 dst_sel:DWORD dst_unused:UNUSED_PAD src0_sel:WORD_1
	v_pk_fma_f32 v[30:31], v[30:31], v[38:39], v[46:47]
	s_nop 0
	v_cvt_pk_f16_f32 v29, v30, v31
	v_cvt_f32_f16_sdwa v31, v40 dst_sel:DWORD dst_unused:UNUSED_PAD src0_sel:WORD_1
	v_cvt_f32_f16_e32 v30, v40
	v_pk_fma_f32 v[24:25], v[24:25], v[34:35], v[30:31]
	s_nop 0
	v_cvt_pk_f16_f32 v30, v24, v25
	v_cvt_f32_f16_sdwa v25, v41 dst_sel:DWORD dst_unused:UNUSED_PAD src0_sel:WORD_1
	v_cvt_f32_f16_e32 v24, v41
	v_cvt_f32_f16_sdwa v35, v37 dst_sel:DWORD dst_unused:UNUSED_PAD src0_sel:WORD_1
	v_cvt_f32_f16_e32 v34, v37
	v_pk_fma_f32 v[24:25], v[26:27], v[34:35], v[24:25]
	s_nop 0
	v_cvt_pk_f16_f32 v31, v24, v25
	v_lshl_add_u64 v[34:35], v[150:151], 1, v[44:45]
	global_store_dwordx4 v[34:35], v[28:31], off
	s_waitcnt vmcnt(12)
	v_mov_b32_e32 v24, v244
	v_mov_b32_e32 v25, v245
	v_mov_b32_e32 v26, v246
	v_mov_b32_e32 v27, v247
	s_cbranch_vccnz .LBB0_184
	v_mov_b32_e32 v28, v248
	v_mov_b32_e32 v29, v249
	v_mov_b32_e32 v30, v250
	v_mov_b32_e32 v31, v251
	s_branch .LBB0_185

;     __device__ __forceinline__ void operator()(const f32x4 (&acc)[2][2][4][2], const Unit& u, int wr, int wc, int fr, int fq) const {
;     ...
;                 for (int bj = 0; bj < 2; ++bj) {
;                     const unsigned row = (unsigned)(row0 + ai * HALF + m * 16);
;                     const int col = col0 + bj * HALF;
;                     const h16x8 gv = *(const h16x8*)(gates + row * DM + col);
;                     h16x8 pv = {0, 0, 0, 0, 0, 0, 0, 0};
;                     if (add) pv = *(const h16x8*)(Mg + row * DM + col);
;                     h16x8 o;
; #pragma unroll
;                     for (int n = 0; n < 2; ++n)
; #pragma unroll
;                         for (int j = 0; j < 4; ++j) o[4 * n + j] = (h16)((float)pv[4 * n + j] + (float)gv[4 * n + j] * acc[ai][bj][m][n][j]);
;                     *(h16x8*)(Mg + row * DM + col) = o;
.LBB0_185:
	s_nop 0
	v_cvt_f32_f16_sdwa v37, v28 dst_sel:DWORD dst_unused:UNUSED_PAD src0_sel:WORD_1
	v_cvt_f32_f16_e32 v36, v28
	v_cvt_f32_f16_sdwa v39, v24 dst_sel:DWORD dst_unused:UNUSED_PAD src0_sel:WORD_1
	v_cvt_f32_f16_e32 v38, v24
	v_cvt_f32_f16_e32 v28, v25
	v_cvt_f32_f16_e32 v24, v26
	v_add_u32_e32 v32, 0x2c000, v32
	v_pk_fma_f32 v[20:21], v[20:21], v[38:39], v[36:37]
	v_cvt_f32_f16_sdwa v37, v29 dst_sel:DWORD dst_unused:UNUSED_PAD src0_sel:WORD_1
	v_cvt_f32_f16_e32 v36, v29
	v_cvt_f32_f16_sdwa v29, v25 dst_sel:DWORD dst_unused:UNUSED_PAD src0_sel:WORD_1
	v_cvt_pk_f16_f32 v20, v20, v21
	v_cvt_f32_f16_sdwa v25, v26 dst_sel:DWORD dst_unused:UNUSED_PAD src0_sel:WORD_1
	s_and_b64 vcc, exec, s[6:7]
	v_pk_fma_f32 v[22:23], v[22:23], v[28:29], v[36:37]
	s_nop 0
	v_cvt_pk_f16_f32 v21, v22, v23
	v_cvt_f32_f16_sdwa v23, v30 dst_sel:DWORD dst_unused:UNUSED_PAD src0_sel:WORD_1
	v_cvt_f32_f16_e32 v22, v30
	v_pk_fma_f32 v[16:17], v[16:17], v[24:25], v[22:23]
	s_nop 0
	v_cvt_pk_f16_f32 v22, v16, v17
	v_cvt_f32_f16_sdwa v17, v31 dst_sel:DWORD dst_unused:UNUSED_PAD src0_sel:WORD_1
	v_cvt_f32_f16_e32 v16, v31
	v_cvt_f32_f16_sdwa v25, v27 dst_sel:DWORD dst_unused:UNUSED_PAD src0_sel:WORD_1
	v_cvt_f32_f16_e32 v24, v27
	v_lshl_add_u64 v[26:27], v[32:33], 1, s[84:85]
	v_pk_fma_f32 v[16:17], v[18:19], v[24:25], v[16:17]
	s_nop 0
	v_cvt_pk_f16_f32 v23, v16, v17
	v_lshl_add_u64 v[16:17], v[32:33], 1, s[16:17]
	global_store_dwordx4 v[34:35], v[20:23], off offset:256
	v_lshl_add_u64 v[24:25], v[150:151], 1, v[16:17]
	s_waitcnt vmcnt(10)
	v_mov_b32_e32 v16, v164
	v_mov_b32_e32 v17, v165
	v_mov_b32_e32 v18, v166
	v_mov_b32_e32 v19, v167
	s_cbranch_vccnz .LBB0_187
	v_lshl_add_u64 v[20:21], v[150:151], 1, v[26:27]
	v_mov_b32_e32 v20, v168
	v_mov_b32_e32 v21, v169
	v_mov_b32_e32 v22, v170
	v_mov_b32_e32 v23, v171
	s_branch .LBB0_188

;     __device__ __forceinline__ void operator()(const f32x4 (&acc)[2][2][4][2], const Unit& u, int wr, int wc, int fr, int fq) const {
;     ...
;                 for (int bj = 0; bj < 2; ++bj) {
;                     const unsigned row = (unsigned)(row0 + ai * HALF + m * 16);
;                     const int col = col0 + bj * HALF;
;                     const h16x8 gv = *(const h16x8*)(gates + row * DM + col);
;                     h16x8 pv = {0, 0, 0, 0, 0, 0, 0, 0};
;                     if (add) pv = *(const h16x8*)(Mg + row * DM + col);
;                     h16x8 o;
; #pragma unroll
;                     for (int n = 0; n < 2; ++n)
; #pragma unroll
;                         for (int j = 0; j < 4; ++j) o[4 * n + j] = (h16)((float)pv[4 * n + j] + (float)gv[4 * n + j] * acc[ai][bj][m][n][j]);
;                     *(h16x8*)(Mg + row * DM + col) = o;
.LBB0_188:
	s_nop 0
	v_cvt_f32_f16_sdwa v29, v20 dst_sel:DWORD dst_unused:UNUSED_PAD src0_sel:WORD_1
	v_cvt_f32_f16_e32 v28, v20
	v_cvt_f32_f16_sdwa v31, v16 dst_sel:DWORD dst_unused:UNUSED_PAD src0_sel:WORD_1
	v_cvt_f32_f16_e32 v30, v16
	v_cvt_f32_f16_e32 v20, v17
	v_cvt_f32_f16_e32 v16, v18
	s_and_b64 vcc, exec, s[6:7]
	v_pk_fma_f32 v[12:13], v[12:13], v[30:31], v[28:29]
	v_cvt_f32_f16_sdwa v29, v21 dst_sel:DWORD dst_unused:UNUSED_PAD src0_sel:WORD_1
	v_cvt_f32_f16_e32 v28, v21
	v_cvt_f32_f16_sdwa v21, v17 dst_sel:DWORD dst_unused:UNUSED_PAD src0_sel:WORD_1
	v_cvt_pk_f16_f32 v12, v12, v13
	v_cvt_f32_f16_sdwa v17, v18 dst_sel:DWORD dst_unused:UNUSED_PAD src0_sel:WORD_1
	v_pk_fma_f32 v[14:15], v[14:15], v[20:21], v[28:29]
	s_nop 0
	v_cvt_pk_f16_f32 v13, v14, v15
	v_cvt_f32_f16_sdwa v15, v22 dst_sel:DWORD dst_unused:UNUSED_PAD src0_sel:WORD_1
	v_cvt_f32_f16_e32 v14, v22
	v_pk_fma_f32 v[8:9], v[8:9], v[16:17], v[14:15]
	s_nop 0
	v_cvt_pk_f16_f32 v14, v8, v9
	v_cvt_f32_f16_sdwa v9, v23 dst_sel:DWORD dst_unused:UNUSED_PAD src0_sel:WORD_1
	v_cvt_f32_f16_e32 v8, v23
	v_cvt_f32_f16_sdwa v17, v19 dst_sel:DWORD dst_unused:UNUSED_PAD src0_sel:WORD_1
	v_cvt_f32_f16_e32 v16, v19
	v_pk_fma_f32 v[8:9], v[10:11], v[16:17], v[8:9]
	s_nop 0
	v_cvt_pk_f16_f32 v15, v8, v9
	v_lshl_add_u64 v[16:17], v[150:151], 1, v[26:27]
	global_store_dwordx4 v[16:17], v[12:15], off
	s_waitcnt vmcnt(8)
	v_mov_b32_e32 v8, v172
	v_mov_b32_e32 v9, v173
	v_mov_b32_e32 v10, v174
	v_mov_b32_e32 v11, v175
	s_cbranch_vccnz .LBB0_190
	v_mov_b32_e32 v12, v176
	v_mov_b32_e32 v13, v177
	v_mov_b32_e32 v14, v178
	v_mov_b32_e32 v15, v179
	s_branch .LBB0_191

; #define PG8_BAR __builtin_amdgcn_s_barrier()
;     __device__ __forceinline__ void operator()(const f32x4 (&acc)[2][2][4][2], const Unit& u, int wr, int wc, int fr, int fq) const {
;     ...
;                 for (int bj = 0; bj < 2; ++bj) {
;                     const unsigned row = (unsigned)(row0 + ai * HALF + m * 16);
;                     const int col = col0 + bj * HALF;
;                     const h16x8 gv = *(const h16x8*)(gates + row * DM + col);
;                     h16x8 pv = {0, 0, 0, 0, 0, 0, 0, 0};
;                     if (add) pv = *(const h16x8*)(Mg + row * DM + col);
;                     h16x8 o;
; #pragma unroll
;                     for (int n = 0; n < 2; ++n)
; #pragma unroll
;                         for (int j = 0; j < 4; ++j) o[4 * n + j] = (h16)((float)pv[4 * n + j] + (float)gv[4 * n + j] * acc[ai][bj][m][n][j]);
;                     *(h16x8*)(Mg + row * DM + col) = o;
; template <class Epi>
; __device__ __forceinline__ void gemm_phase(LAS unsigned char* lds, const Gemm g, const StaticOrder& S, const Epi& E) {
;     ...
;         if (wr == 0) PG8_BAR;
;         E(acc, cur, wr, wc, fr, fq);
;         if (!has_next) break;
; #pragma unroll
;         for (int a = 0; a < 2; ++a)
; #pragma unroll
;             for (int b = 0; b < 2; ++b)
; #pragma unroll
;                 for (int m = 0; m < 4; ++m)
; #pragma unroll
;                     for (int n = 0; n < 2; ++n) acc[a][b][m][n] = (f32x4){0.f, 0.f, 0.f, 0.f};
;         cur = nxt; cA = nA; cB = nB; ++ui;
;         if (wr == 1) PG8_BAR;
.LBB0_191:
	s_nop 0
	v_cvt_f32_f16_sdwa v19, v12 dst_sel:DWORD dst_unused:UNUSED_PAD src0_sel:WORD_1
	v_cvt_f32_f16_e32 v18, v12
	v_cvt_f32_f16_sdwa v23, v13 dst_sel:DWORD dst_unused:UNUSED_PAD src0_sel:WORD_1
	v_cvt_f32_f16_e32 v22, v13
	v_cvt_f32_f16_sdwa v13, v9 dst_sel:DWORD dst_unused:UNUSED_PAD src0_sel:WORD_1
	v_cvt_f32_f16_e32 v12, v9
	v_cvt_f32_f16_sdwa v21, v8 dst_sel:DWORD dst_unused:UNUSED_PAD src0_sel:WORD_1
	v_cvt_f32_f16_e32 v20, v8
	v_cvt_f32_f16_sdwa v9, v14 dst_sel:DWORD dst_unused:UNUSED_PAD src0_sel:WORD_1
	v_pk_fma_f32 v[6:7], v[6:7], v[12:13], v[22:23]
	v_cvt_f32_f16_e32 v8, v14
	v_cvt_f32_f16_sdwa v13, v10 dst_sel:DWORD dst_unused:UNUSED_PAD src0_sel:WORD_1
	v_cvt_f32_f16_e32 v12, v10
	v_pk_fma_f32 v[4:5], v[4:5], v[20:21], v[18:19]
	v_cvt_f32_f16_sdwa v19, v15 dst_sel:DWORD dst_unused:UNUSED_PAD src0_sel:WORD_1
	v_cvt_f32_f16_e32 v18, v15
	v_cvt_f32_f16_sdwa v15, v11 dst_sel:DWORD dst_unused:UNUSED_PAD src0_sel:WORD_1
	v_cvt_f32_f16_e32 v14, v11
	v_pk_fma_f32 v[0:1], v[0:1], v[12:13], v[8:9]
	v_cvt_pk_f16_f32 v4, v4, v5
	v_cvt_pk_f16_f32 v5, v6, v7
	v_cvt_pk_f16_f32 v6, v0, v1
	v_pk_fma_f32 v[0:1], v[2:3], v[14:15], v[18:19]
	s_and_b64 vcc, exec, s[4:5]
	v_cvt_pk_f16_f32 v7, v0, v1
	s_mov_b64 s[4:5], -1
	global_store_dwordx4 v[16:17], v[4:7], off offset:256
	s_cbranch_vccnz .LBB0_128
	s_andn2_b64 vcc, exec, s[14:15]
	s_cbranch_vccnz .LBB0_127
	s_barrier
	s_branch .LBB0_127
